# attention + mem-attention unit prologue: gain abs-max computed with one round trip of lane-distributed loads + DPP row reduction instead of 8 dependent uniform-load iterations
# speedup vs baseline: 1.0180x; 1.0015x over previous
.LBB0_1007:
	s_mov_b64 s[4:5], s[0:1]
	s_load_dwordx2 s[8:9], s[4:5], 0xe8
	s_mov_b64 s[4:5], s[0:1]
	s_load_dwordx2 s[30:31], s[4:5], 0x10
	s_mov_b64 s[4:5], s[0:1]
	s_load_dwordx2 s[6:7], s[4:5], 0xe8
	s_mov_b64 s[4:5], s[0:1]
	s_mov_b64 s[10:11], s[0:1]
	s_load_dwordx2 s[4:5], s[4:5], 0xe8
	s_load_dwordx2 s[34:35], s[10:11], 0xe8
	s_mov_b64 s[10:11], 0
	s_waitcnt vmcnt(2)
	v_and_b32_e32 v0, 15, v224
	v_and_b32_e32 v1, 7, v224
	v_lshlrev_b32_e32 v0, 4, v0
	v_lshlrev_b32_e32 v1, 4, v1
	s_mov_b32 s12, s39
	s_mov_b32 s13, s38
	global_load_dwordx4 v[2:5], v0, s[44:45]
	global_load_dwordx4 v[6:9], v1, s[44:45] offset:256
	global_load_dwordx4 v[10:13], v0, s[12:13]
	global_load_dwordx4 v[14:17], v1, s[12:13] offset:256
	s_waitcnt vmcnt(2)
	v_max3_f32 v18, |v2|, |v3|, |v4|
	v_max3_f32 v19, |v6|, |v7|, |v8|
	v_max3_f32 v18, v18, |v5|, |v9|
	s_waitcnt vmcnt(0)
	v_max3_f32 v20, |v10|, |v11|, |v12|
	v_max3_f32 v21, |v14|, |v15|, |v16|
	v_max3_f32 v20, v20, |v13|, |v17|
	v_max_f32_e32 v18, v18, v19
	v_max_f32_e32 v20, v20, v21
	s_nop 0
	v_max_f32_dpp v18, v18, v18 row_ror:8 row_mask:0xf bank_mask:0xf
	v_max_f32_dpp v20, v20, v20 row_ror:8 row_mask:0xf bank_mask:0xf
	s_nop 0
	v_max_f32_dpp v18, v18, v18 row_ror:4 row_mask:0xf bank_mask:0xf
	v_max_f32_dpp v20, v20, v20 row_ror:4 row_mask:0xf bank_mask:0xf
	s_nop 0
	v_max_f32_dpp v18, v18, v18 row_ror:2 row_mask:0xf bank_mask:0xf
	v_max_f32_dpp v20, v20, v20 row_ror:2 row_mask:0xf bank_mask:0xf
	s_nop 0
	v_max_f32_dpp v1, v18, v18 row_ror:1 row_mask:0xf bank_mask:0xf
	v_max_f32_dpp v0, v20, v20 row_ror:1 row_mask:0xf bank_mask:0xf
	s_ashr_i32 s3, s50, 3
	s_and_b32 s3, s3, -8
	v_readlane_b32 s10, v255, 12
	s_or_b32 s10, s3, s10
	s_mul_hi_i32 s3, s10, 0x2aaaaaab
	s_lshr_b32 s11, s3, 31
	s_ashr_i32 s3, s3, 1
	s_add_i32 s3, s3, s11
	s_mul_i32 s11, s3, 12
	s_sub_i32 s51, s10, s11
	s_mul_i32 s12, s51, 0x60
	s_ashr_i32 s13, s12, 31
	s_lshl_b64 s[12:13], s[12:13], 1
	s_waitcnt lgkmcnt(0)
	s_add_u32 s8, s8, s12
	s_addc_u32 s9, s9, s13
	s_add_u32 s40, s8, 0x14200000
	s_addc_u32 s41, s9, 0
	s_lshl_b32 s8, s50, 8
	s_and_b32 s12, s8, 0x3f00
	s_ashr_i32 s11, s10, 31
	s_lshl_b32 s3, s3, 14
	s_mul_i32 s14, s10, 0x300000
	s_lshl_b64 s[8:9], s[10:11], 21
	s_or_b32 s47, s3, s12
	s_mul_hi_i32 s13, s10, 0x300000
	s_add_u32 s3, s6, s14
	s_addc_u32 s6, s7, s13
	s_add_u32 s42, s3, 0x18a00000
	s_addc_u32 s43, s6, 0
	s_add_u32 s3, s4, s8
	v_mul_f32_e32 v0, v1, v0
	s_addc_u32 s4, s5, s9
	v_mul_f32_e32 v0, 0x42c00000, v0
	s_add_u32 s62, s3, 0x5200000
	v_mul_f32_e32 v0, 0x3e16c740, v0
	s_mov_b32 s3, 0x3f83d70a
	v_fma_f32 v176, v0, s3, 0.5
	s_mov_b32 s3, 0x42400000
	v_cmp_ngt_f32_e32 vcc, s3, v176
	s_addc_u32 s63, s4, 0
	s_mov_b64 s[4:5], -1
	s_and_b64 vcc, exec, vcc
	s_cbranch_vccz .LBB0_1034
	v_mov_b32_e32 v0, v224
	v_mov_b32_e32 v100, v113
	v_ashrrev_i32_e32 v1, 31, v0
	v_lshl_add_u64 v[2:3], v[0:1], 4, s[42:43]
	global_load_dwordx4 v[12:15], v[2:3], off
	v_mov_b32_e32 v101, v113
	v_add_u32_e32 v70, 0x200, v0
	v_mov_b32_e32 v102, v113
	v_mov_b32_e32 v103, v113
	v_mov_b64_e32 v[96:97], v[100:101]
	v_cmp_lt_i32_e64 s[6:7], s2, v0
	v_cmp_gt_i32_e64 s[4:5], s89, v0
	v_ashrrev_i32_e32 v71, 31, v70
	v_mov_b64_e32 v[98:99], v[102:103]
	s_and_saveexec_b64 s[8:9], s[4:5]
	s_cbranch_execz .LBB0_1012
	v_lshl_add_u64 v[2:3], v[70:71], 4, s[42:43]
	global_load_dwordx4 v[96:99], v[2:3], off

.LBB0_1257:
	s_mov_b64 s[4:5], s[0:1]
	s_load_dwordx2 s[14:15], s[4:5], 0xe8
	s_mov_b64 s[4:5], s[0:1]
	s_load_dwordx2 s[6:7], s[4:5], 0x48
	s_mov_b64 s[4:5], s[0:1]
	s_load_dwordx2 s[16:17], s[4:5], 0x50
	s_mov_b64 s[4:5], s[0:1]
	s_mov_b64 s[4:5], s[0:1]
	s_load_dwordx2 s[8:9], s[4:5], 0xe8
	s_mov_b64 s[4:5], s[0:1]
	s_mov_b64 s[12:13], s[0:1]
	s_load_dwordx2 s[4:5], s[4:5], 0xe8
	s_load_dwordx2 s[12:13], s[12:13], 0xe8
	v_readlane_b32 s20, v255, 28
	v_readlane_b32 s21, v255, 29
	s_waitcnt lgkmcnt(0)
	s_add_u32 s18, s6, s20
	s_addc_u32 s19, s7, s21
	s_add_u32 s20, s16, s20
	s_addc_u32 s21, s17, s21
	s_mov_b64 s[16:17], 0
	s_waitcnt vmcnt(2)
	v_and_b32_e32 v0, 15, v224
	v_lshlrev_b32_e32 v0, 4, v0
	global_load_dwordx4 v[2:5], v0, s[18:19]
	global_load_dwordx4 v[6:9], v0, s[20:21]
	s_waitcnt vmcnt(1)
	v_max3_f32 v10, |v2|, |v3|, |v4|
	s_waitcnt vmcnt(0)
	v_max3_f32 v12, |v6|, |v7|, |v8|
	v_max_f32_e64 v10, v10, |v5|
	v_max_f32_e64 v12, v12, |v9|
	s_nop 0
	v_max_f32_dpp v10, v10, v10 row_ror:8 row_mask:0xf bank_mask:0xf
	v_max_f32_dpp v12, v12, v12 row_ror:8 row_mask:0xf bank_mask:0xf
	s_nop 0
	v_max_f32_dpp v10, v10, v10 row_ror:4 row_mask:0xf bank_mask:0xf
	v_max_f32_dpp v12, v12, v12 row_ror:4 row_mask:0xf bank_mask:0xf
	s_nop 0
	v_max_f32_dpp v10, v10, v10 row_ror:2 row_mask:0xf bank_mask:0xf
	v_max_f32_dpp v12, v12, v12 row_ror:2 row_mask:0xf bank_mask:0xf
	s_nop 0
	v_max_f32_dpp v1, v10, v10 row_ror:1 row_mask:0xf bank_mask:0xf
	v_max_f32_dpp v0, v12, v12 row_ror:1 row_mask:0xf bank_mask:0xf
	s_ashr_i32 s3, s30, 8
	s_lshl_b32 s16, s3, 2
	s_bfe_u32 s31, s30, 0x20006
	s_add_i32 s16, s16, s24
	s_or_b32 s20, s16, s31
	s_ashr_i32 s21, s20, 31
	s_add_u32 s14, s14, s25
	s_addc_u32 s15, s15, 0
	s_lshl_b32 s16, s31, 7
	s_add_u32 s14, s14, s16
	s_addc_u32 s15, s15, 0
	s_add_u32 s18, s14, 0x9200000
	s_addc_u32 s19, s15, 0
	s_lshl_b32 s14, s30, 8
	s_and_b32 s14, s14, 0x3f00
	s_add_u32 s16, s6, s10
	s_addc_u32 s17, s7, s11
	s_lshl_b32 s3, s3, 14
	s_lshl_b64 s[6:7], s[20:21], 15
	s_or_b32 s34, s3, s14
	s_add_u32 s3, s8, s6
	s_addc_u32 s8, s9, s7
	s_add_u32 s14, s3, 0x1000000
	s_addc_u32 s15, s8, 0
	s_add_u32 s3, s4, s6
	v_mul_f32_e32 v0, v1, v0
	s_addc_u32 s4, s5, s7
	v_mul_f32_e32 v0, 0x42800000, v0
	s_add_u32 s20, s3, 0x1100000
	v_mul_f32_e32 v0, 0x3e38aa3b, v0
	s_mov_b32 s3, 0x3f83d70a
	v_fma_f32 v159, v0, s3, 0.5
	s_mov_b32 s3, 0x42400000
	v_cmp_ngt_f32_e32 vcc, s3, v159
	s_addc_u32 s21, s4, 0
	s_mov_b64 s[4:5], -1
	s_and_b64 vcc, exec, vcc
	s_cbranch_vccz .LBB0_1285
	v_mov_b32_e32 v0, v224
	s_nop 0
	v_ashrrev_i32_e32 v1, 31, v0
	v_lshl_add_u64 v[2:3], v[0:1], 4, s[14:15]
	global_load_dwordx4 v[12:15], v[2:3], off
	v_lshlrev_b64 v[56:57], 3, v[0:1]
	v_cmp_gt_i32_e64 s[4:5], 0, v0
	v_cmp_lt_i32_e64 s[6:7], -1, v0
	v_lshl_add_u64 v[54:55], v[56:57], 1, s[14:15]
	s_and_saveexec_b64 s[8:9], s[6:7]
	s_xor_b64 s[8:9], exec, s[8:9]
	s_cbranch_execz .LBB0_1262
	v_add_co_u32_e32 v2, vcc, 0x2000, v54
	s_nop 1
	v_addc_co_u32_e32 v3, vcc, 0, v55, vcc
	global_load_dwordx4 v[8:11], v[2:3], off
